# prep RMSNorm loop: 4 loop-invariant gain loads hoisted out of the loop into v[96:111]; removes 3 vmcnt(0) waits per iteration that sat behind the bf16 stores
# baseline (speedup 1.0000x reference)
; DI int tidx() { int t = threadIdx.x; asm volatile("" : "+v"(t)); return t; }
; DI void rms_rows(const float* X, const float* g, bf16_t* out, int nrows) {
;   const int wid = tidx() >> 6, lane = tidx() & 63; const int stride = gridDim.x * 8;
;   for (int r = blockIdx.x * 8 + wid; r < nrows; r += 2 * stride) {
;     const int r2 = r + stride; const bool has2 = r2 < nrows;
;     const f32x4* xa = (const f32x4*)(X + (size_t)r * DM); const f32x4* xb = (const f32x4*)(X + (size_t)(has2 ? r2 : r) * DM);
;     f32x4 va[4], vb[4]; float sa = 0.f, sb = 0.f;
; #pragma unroll
;     for (int i = 0; i < 4; ++i) { va[i] = __builtin_nontemporal_load(xa + lane + 64 * i); vb[i] = __builtin_nontemporal_load(xb + lane + 64 * i); }
; #pragma unroll
;     for (int i = 0; i < 4; ++i) { sa += va[i][0] * va[i][0] + va[i][1] * va[i][1] + va[i][2] * va[i][2] + va[i][3] * va[i][3]; sb += vb[i][0] * vb[i][0] + vb[i][1] * vb[i][1] + vb[i][2] * vb[i][2] + vb[i][3] * vb[i][3]; }
;     sa = wave_sum(sa); sb = wave_sum(sb);
;     const float ra = rsqrtf(sa * (1.0f / DM) + RMS_EPS), rb = rsqrtf(sb * (1.0f / DM) + RMS_EPS);
; #pragma unroll
;     for (int i = 0; i < 4; ++i) { const f32x4 gg = ((const f32x4*)g)[lane + 64 * i];
.LBB0_51:
	s_or_b64 exec, exec, s[0:1]
	s_add_u32 s44, s74, 0x4000000
	v_mov_b32_e32 v0, v212
	v_readlane_b32 s0, v254, 0
	s_addc_u32 s45, s75, 0
	s_lshl_b32 s3, s0, 3
	v_ashrrev_i32_e32 v1, 6, v0
	v_add_u32_e32 v56, s3, v1
	s_mov_b32 s13, 0x8000
	v_mov_b32_e32 v0, v212
	s_lshl_b32 s2, s90, 3
	v_cmp_gt_i32_e32 vcc, s13, v56
	v_mbcnt_lo_u32_b32 v154, -1, 0
	s_and_saveexec_b64 s[8:9], vcc
	s_cbranch_execz .LBB0_62
	v_mbcnt_hi_u32_b32 v1, -1, v154
	v_and_b32_e32 v3, 64, v1
	v_xor_b32_e32 v2, 32, v1
	v_add_u32_e32 v3, 64, v3
	v_cmp_lt_i32_e32 vcc, v2, v3
	v_and_b32_e32 v0, 63, v0
	v_lshlrev_b32_e32 v36, 4, v0
	v_cndmask_b32_e32 v2, v1, v2, vcc
	v_lshlrev_b32_e32 v43, 2, v2
	v_xor_b32_e32 v2, 16, v1
	v_cmp_lt_i32_e32 vcc, v2, v3
	v_lshlrev_b32_e32 v0, 2, v0
	v_mov_b32_e32 v37, 0
	v_cndmask_b32_e32 v2, v1, v2, vcc
	v_lshlrev_b32_e32 v45, 2, v2
	v_xor_b32_e32 v2, 8, v1
	v_cmp_lt_i32_e32 vcc, v2, v3
	v_lshlrev_b32_e32 v50, 1, v0
	v_lshl_add_u64 v[38:39], s[16:17], 0, v[36:37]
	v_cndmask_b32_e32 v2, v1, v2, vcc
	v_lshlrev_b32_e32 v47, 2, v2
	v_xor_b32_e32 v2, 4, v1
	v_cmp_lt_i32_e32 vcc, v2, v3
	v_lshl_add_u64 v[40:41], s[22:23], 0, v[36:37]
	v_or_b32_e32 v42, 0x100, v0
	v_cndmask_b32_e32 v2, v1, v2, vcc
	v_lshlrev_b32_e32 v49, 2, v2
	v_xor_b32_e32 v2, 2, v1
	v_cmp_lt_i32_e32 vcc, v2, v3
	v_or_b32_e32 v44, 0x200, v0
	v_or_b32_e32 v46, 0x300, v0
	v_cndmask_b32_e32 v2, v1, v2, vcc
	v_lshlrev_b32_e32 v64, 2, v2
	v_xor_b32_e32 v2, 1, v1
	v_cmp_lt_i32_e32 vcc, v2, v3
	s_mov_b64 s[10:11], 0
	s_mov_b32 s12, 0x3a800000
	v_cndmask_b32_e32 v1, v1, v2, vcc
	v_lshlrev_b32_e32 v65, 2, v1
	v_mov_b32_e32 v48, 0x358637bd
	s_mov_b32 s14, 0x800000
	v_mov_b32_e32 v52, v50
	v_mov_b32_e32 v53, v37
	s_movk_i32 s15, 0x7fff
	global_load_dwordx4 v[96:99], v[40:41], off
	global_load_dwordx4 v[100:103], v[40:41], off offset:1024
	global_load_dwordx4 v[104:107], v[40:41], off offset:2048
	global_load_dwordx4 v[108:111], v[40:41], off offset:3072
	s_branch .LBB0_54

; DI int tidx() { int t = threadIdx.x; asm volatile("" : "+v"(t)); return t; }
; DI void st_bf4(bf16_t* p, f32x4 v) { u32x2 w; w.x = pk2(v[0], v[1]); w.y = pk2(v[2], v[3]); *(u32x2*)p = w; }
; DI void rms_rows(const float* X, const float* g, bf16_t* out, int nrows) {
;   const int wid = tidx() >> 6, lane = tidx() & 63; const int stride = gridDim.x * 8;
;   for (int r = blockIdx.x * 8 + wid; r < nrows; r += 2 * stride) {
;     const int r2 = r + stride; const bool has2 = r2 < nrows;
;     const f32x4* xa = (const f32x4*)(X + (size_t)r * DM); const f32x4* xb = (const f32x4*)(X + (size_t)(has2 ? r2 : r) * DM);
;     f32x4 va[4], vb[4]; float sa = 0.f, sb = 0.f;
; #pragma unroll
;     for (int i = 0; i < 4; ++i) { va[i] = __builtin_nontemporal_load(xa + lane + 64 * i); vb[i] = __builtin_nontemporal_load(xb + lane + 64 * i); }
; #pragma unroll
;     for (int i = 0; i < 4; ++i) { sa += va[i][0] * va[i][0] + va[i][1] * va[i][1] + va[i][2] * va[i][2] + va[i][3] * va[i][3]; sb += vb[i][0] * vb[i][0] + vb[i][1] * vb[i][1] + vb[i][2] * vb[i][2] + vb[i][3] * vb[i][3]; }
;     sa = wave_sum(sa); sb = wave_sum(sb);
;     const float ra = rsqrtf(sa * (1.0f / DM) + RMS_EPS), rb = rsqrtf(sb * (1.0f / DM) + RMS_EPS);
; #pragma unroll
;     for (int i = 0; i < 4; ++i) { const f32x4 gg = ((const f32x4*)g)[lane + 64 * i];
;       st_bf4(out + (size_t)r * DM + (lane + 64 * i) * 4, va[i] * ra * gg);
.LBB0_54:
	v_ashrrev_i32_e32 v57, 31, v56
	v_lshlrev_b64 v[0:1], 12, v[56:57]
	v_add_u32_e32 v54, s2, v56
	v_lshl_add_u64 v[0:1], v[38:39], 0, v[0:1]
	v_cmp_gt_i32_e32 vcc, s13, v54
	global_load_dwordx4 v[28:31], v[0:1], off nt
	global_load_dwordx4 v[20:23], v[0:1], off offset:1024 nt
	global_load_dwordx4 v[12:15], v[0:1], off offset:2048 nt
	global_load_dwordx4 v[4:7], v[0:1], off offset:3072 nt
	v_cndmask_b32_e32 v0, v56, v54, vcc
	v_ashrrev_i32_e32 v1, 31, v0
	v_lshlrev_b64 v[0:1], 12, v[0:1]
	v_lshl_add_u64 v[0:1], v[38:39], 0, v[0:1]
	global_load_dwordx4 v[24:27], v[0:1], off nt
	global_load_dwordx4 v[16:19], v[0:1], off offset:1024 nt
	global_load_dwordx4 v[8:11], v[0:1], off offset:2048 nt
	s_nop 0
	global_load_dwordx4 v[0:3], v[0:1], off offset:3072 nt
	s_nop 0
	v_lshlrev_b64 v[56:57], 11, v[56:57]
	v_ashrrev_i32_e32 v55, 31, v54
	s_waitcnt vmcnt(7)
	v_mov_b32_e32 v60, v29
	s_waitcnt vmcnt(6)
	v_mov_b32_e32 v61, v21
	s_waitcnt vmcnt(5)
	v_mov_b32_e32 v70, v13
	s_waitcnt vmcnt(4)
	v_mov_b32_e32 v71, v5
	v_mov_b32_e32 v58, v28
	v_mov_b32_e32 v59, v20
	v_mov_b32_e32 v68, v12
	v_mov_b32_e32 v69, v4
	v_pk_mul_f32 v[60:61], v[60:61], v[60:61]
	v_pk_mul_f32 v[70:71], v[70:71], v[70:71]
	v_mov_b32_e32 v62, v30
	v_mov_b32_e32 v63, v22
	v_pk_fma_f32 v[58:59], v[58:59], v[58:59], v[60:61]
	v_pk_fma_f32 v[60:61], v[68:69], v[68:69], v[70:71]
	s_waitcnt vmcnt(3)
	v_mov_b32_e32 v70, v25
	s_waitcnt vmcnt(2)
	v_mov_b32_e32 v71, v17
	v_mov_b32_e32 v68, v24
	v_mov_b32_e32 v69, v16
	s_waitcnt vmcnt(1)
	v_mov_b32_e32 v82, v9
	s_waitcnt vmcnt(0)
	v_mov_b32_e32 v83, v1
	v_pk_fma_f32 v[58:59], v[62:63], v[62:63], v[58:59]
	v_pk_mul_f32 v[62:63], v[70:71], v[70:71]
	v_mov_b32_e32 v66, v31
	v_mov_b32_e32 v67, v23
	v_mov_b32_e32 v76, v26
	v_mov_b32_e32 v77, v18
	v_mov_b32_e32 v80, v8
	v_mov_b32_e32 v81, v0
	v_pk_mul_f32 v[70:71], v[82:83], v[82:83]
	v_pk_fma_f32 v[62:63], v[68:69], v[68:69], v[62:63]
	v_mov_b32_e32 v72, v14
	v_mov_b32_e32 v73, v6
	v_mov_b32_e32 v78, v27
	v_mov_b32_e32 v79, v19
	v_mov_b32_e32 v84, v10
	v_mov_b32_e32 v85, v2
	v_pk_fma_f32 v[58:59], v[66:67], v[66:67], v[58:59]
	v_pk_fma_f32 v[66:67], v[80:81], v[80:81], v[70:71]
	v_pk_fma_f32 v[62:63], v[76:77], v[76:77], v[62:63]
	v_mov_b32_e32 v74, v15
	v_mov_b32_e32 v75, v7
	v_mov_b32_e32 v86, v11
	v_mov_b32_e32 v87, v3
	v_pk_fma_f32 v[60:61], v[72:73], v[72:73], v[60:61]
	v_pk_fma_f32 v[66:67], v[84:85], v[84:85], v[66:67]
	v_pk_fma_f32 v[62:63], v[78:79], v[78:79], v[62:63]
	v_pk_fma_f32 v[60:61], v[74:75], v[74:75], v[60:61]
	v_mov_b32_e32 v69, v58
	v_pk_fma_f32 v[66:67], v[86:87], v[86:87], v[66:67]
	v_mov_b32_e32 v68, v62
	v_mov_b32_e32 v58, v63
	v_mov_b32_e32 v71, v60
	v_mov_b32_e32 v70, v66
	v_pk_add_f32 v[58:59], v[68:69], v[58:59]
	v_mov_b32_e32 v60, v67
	v_pk_add_f32 v[58:59], v[58:59], v[70:71]
	s_nop 0
	v_pk_add_f32 v[58:59], v[58:59], v[60:61]
	ds_bpermute_b32 v61, v43, v59
	ds_bpermute_b32 v60, v43, v58
	s_waitcnt lgkmcnt(0)
	v_pk_add_f32 v[58:59], v[58:59], v[60:61]
	ds_bpermute_b32 v61, v45, v59
	ds_bpermute_b32 v60, v45, v58
	s_waitcnt lgkmcnt(0)
	v_pk_add_f32 v[58:59], v[58:59], v[60:61]
	ds_bpermute_b32 v61, v47, v59
	ds_bpermute_b32 v60, v47, v58
	s_waitcnt lgkmcnt(0)
	v_pk_add_f32 v[58:59], v[58:59], v[60:61]
	ds_bpermute_b32 v61, v49, v59
	ds_bpermute_b32 v60, v49, v58
	s_waitcnt lgkmcnt(0)
	v_pk_add_f32 v[58:59], v[58:59], v[60:61]
	ds_bpermute_b32 v61, v64, v59
	ds_bpermute_b32 v60, v64, v58
	s_waitcnt lgkmcnt(0)
	v_pk_add_f32 v[58:59], v[58:59], v[60:61]
	ds_bpermute_b32 v63, v65, v59
	ds_bpermute_b32 v62, v65, v58
	v_lshl_add_u64 v[60:61], s[44:45], 0, v[56:57]
	v_lshlrev_b64 v[56:57], 11, v[54:55]
	v_lshl_add_u64 v[66:67], v[60:61], 0, v[52:53]
	s_waitcnt lgkmcnt(0)
	v_pk_add_f32 v[58:59], v[58:59], v[62:63]
	s_nop 0
	v_pk_fma_f32 v[58:59], v[58:59], s[12:13], v[48:49] op_sel_hi:[1,0,0]
	s_nop 0
	v_mul_f32_e32 v36, 0x4b800000, v59
	v_cmp_gt_f32_e64 s[4:5], s14, v59
	v_mul_f32_e32 v51, 0x4b800000, v58
	v_cmp_gt_f32_e64 s[6:7], s14, v58
	v_cndmask_b32_e64 v36, v59, v36, s[4:5]
	v_rsq_f32_e32 v36, v36
	v_cndmask_b32_e64 v51, v58, v51, s[6:7]
	v_rsq_f32_e32 v51, v51
	v_lshl_add_u64 v[58:59], s[44:45], 0, v[56:57]
	v_mul_f32_e32 v55, 0x45800000, v36
	v_cndmask_b32_e64 v62, v36, v55, s[4:5]
	v_mul_f32_e32 v56, 0x45800000, v51
	v_pk_mul_f32 v[28:29], v[28:29], v[62:63] op_sel_hi:[1,0]
	v_pk_mul_f32 v[30:31], v[30:31], v[62:63] op_sel_hi:[1,0]
	v_cndmask_b32_e64 v56, v51, v56, s[6:7]
	s_waitcnt vmcnt(0)
	v_pk_mul_f32 v[30:31], v[98:99], v[30:31]
	v_pk_mul_f32 v[28:29], v[96:97], v[28:29]
	v_mov_b32_e32 v57, v56
	v_cvt_pk_bf16_f32 v28, v28, v29
	v_cvt_pk_bf16_f32 v29, v30, v31
	global_store_dwordx2 v[66:67], v[28:29], off
	s_and_saveexec_b64 s[0:1], vcc
	s_cbranch_execz .LBB0_56
	v_mov_b32_e32 v30, v56
	v_mov_b32_e32 v31, v56
	v_pk_mul_f32 v[26:27], v[26:27], v[30:31]
	v_pk_mul_f32 v[24:25], v[24:25], v[56:57]
	v_mov_b32_e32 v51, v37
	v_pk_mul_f32 v[26:27], v[98:99], v[26:27]
	v_pk_mul_f32 v[24:25], v[96:97], v[24:25]
	v_lshl_add_u64 v[28:29], v[58:59], 0, v[50:51]
	v_cvt_pk_bf16_f32 v24, v24, v25
	v_cvt_pk_bf16_f32 v25, v26, v27
	global_store_dwordx2 v[28:29], v[24:25], off
; DI void st_bf4(bf16_t* p, f32x4 v) { u32x2 w; w.x = pk2(v[0], v[1]); w.y = pk2(v[2], v[3]); *(u32x2*)p = w; }
; DI void rms_rows(const float* X, const float* g, bf16_t* out, int nrows) {
;     ...
; #pragma unroll
;     for (int i = 0; i < 4; ++i) { const f32x4 gg = ((const f32x4*)g)[lane + 64 * i];
;       st_bf4(out + (size_t)r * DM + (lane + 64 * i) * 4, va[i] * ra * gg);
;       if (has2) st_bf4(out + (size_t)r2 * DM + (lane + 64 * i) * 4, vb[i] * rb * gg); }
.LBB0_56:
	s_or_b64 exec, exec, s[0:1]
	v_mov_b32_e32 v63, v62
	v_mov_b32_e32 v28, v62
	v_mov_b32_e32 v29, v62
	v_pk_mul_f32 v[22:23], v[22:23], v[28:29]
	v_pk_mul_f32 v[20:21], v[20:21], v[62:63]
	v_lshlrev_b32_e32 v36, 1, v42
	v_lshl_add_u64 v[30:31], v[60:61], 0, v[36:37]
	v_pk_mul_f32 v[22:23], v[22:23], v[102:103]
	v_pk_mul_f32 v[20:21], v[20:21], v[100:101]
	s_nop 0
	v_cvt_pk_bf16_f32 v20, v20, v21
	v_cvt_pk_bf16_f32 v21, v22, v23
	global_store_dwordx2 v[30:31], v[20:21], off
	s_and_saveexec_b64 s[0:1], vcc
	s_cbranch_execz .LBB0_58
	v_mov_b32_e32 v22, v56
	v_mov_b32_e32 v23, v56
	v_pk_mul_f32 v[18:19], v[18:19], v[22:23]
	v_pk_mul_f32 v[16:17], v[16:17], v[56:57]
	v_pk_mul_f32 v[18:19], v[18:19], v[102:103]
	v_pk_mul_f32 v[16:17], v[16:17], v[100:101]
	v_lshl_add_u64 v[20:21], v[58:59], 0, v[36:37]
	v_cvt_pk_bf16_f32 v16, v16, v17
	v_cvt_pk_bf16_f32 v17, v18, v19
	global_store_dwordx2 v[20:21], v[16:17], off
.LBB0_58:
	s_or_b64 exec, exec, s[0:1]
	v_pk_mul_f32 v[14:15], v[14:15], v[28:29]
	v_pk_mul_f32 v[12:13], v[12:13], v[62:63]
	v_lshlrev_b32_e32 v36, 1, v44
	v_lshl_add_u64 v[20:21], v[60:61], 0, v[36:37]
	v_pk_mul_f32 v[14:15], v[14:15], v[106:107]
	v_pk_mul_f32 v[12:13], v[12:13], v[104:105]
	s_nop 0
	v_cvt_pk_bf16_f32 v12, v12, v13
	v_cvt_pk_bf16_f32 v13, v14, v15
	global_store_dwordx2 v[20:21], v[12:13], off
	s_and_saveexec_b64 s[0:1], vcc
	s_cbranch_execz .LBB0_60
	v_mov_b32_e32 v14, v56
	v_mov_b32_e32 v15, v56
	v_pk_mul_f32 v[10:11], v[10:11], v[14:15]
	v_pk_mul_f32 v[8:9], v[8:9], v[56:57]
	v_pk_mul_f32 v[10:11], v[10:11], v[106:107]
	v_pk_mul_f32 v[8:9], v[8:9], v[104:105]
	v_lshl_add_u64 v[12:13], v[58:59], 0, v[36:37]
	v_cvt_pk_bf16_f32 v8, v8, v9
	v_cvt_pk_bf16_f32 v9, v10, v11
	global_store_dwordx2 v[12:13], v[8:9], off
.LBB0_60:
	s_or_b64 exec, exec, s[0:1]
	v_mov_b32_e32 v12, v62
	v_mov_b32_e32 v13, v62
	v_pk_mul_f32 v[4:5], v[4:5], v[62:63]
	v_pk_mul_f32 v[6:7], v[6:7], v[12:13]
	v_lshlrev_b32_e32 v36, 1, v46
	v_lshl_add_u64 v[14:15], v[60:61], 0, v[36:37]
	v_pk_mul_f32 v[6:7], v[6:7], v[110:111]
	v_pk_mul_f32 v[4:5], v[4:5], v[108:109]
	s_nop 0
	v_cvt_pk_bf16_f32 v4, v4, v5
	v_cvt_pk_bf16_f32 v5, v6, v7
	global_store_dwordx2 v[14:15], v[4:5], off
	s_and_saveexec_b64 s[0:1], vcc
	s_cbranch_execz .LBB0_53
	v_mov_b32_e32 v6, v56
	v_mov_b32_e32 v7, v56
	v_pk_mul_f32 v[2:3], v[2:3], v[6:7]
	v_pk_mul_f32 v[0:1], v[0:1], v[56:57]
	v_pk_mul_f32 v[2:3], v[2:3], v[110:111]
	v_pk_mul_f32 v[0:1], v[0:1], v[108:109]
	v_lshl_add_u64 v[4:5], v[58:59], 0, v[36:37]
	v_cvt_pk_bf16_f32 v0, v0, v1
	v_cvt_pk_bf16_f32 v1, v2, v3
	global_store_dwordx2 v[4:5], v[0:1], off
	s_branch .LBB0_53
